# LRU pass-1: six per-iteration gate/softplus parameter loads hoisted to the top of the channel-tile loop
# speedup vs baseline: 1.0239x; 1.0070x over previous
; #define GAS __attribute__((address_space(1)))
; __device__ __forceinline__ int lru_pass1(const Params& P, int l, LAS unsigned char* lds, unsigned* qw) {
;     ...
;         for (int jt = 0; jt < 4; ++jt) { const int cl = 16 * jt + fr, c = h * 64 + cl;
;             f32x4 acc[4][4];
; #pragma unroll
;             for (int mt = 0; mt < 4; ++mt)
; #pragma unroll
;                 for (int dt = 0; dt < 4; ++dt) acc[mt][dt] = (f32x4){0.f, 0.f, 0.f, 0.f};
;             bf16x8 Bfr[4][2];
; #pragma unroll
;             for (int dt = 0; dt < 4; ++dt)
; #pragma unroll
;                 for (int kk = 0; kk < 2; ++kk) Bfr[dt][kk] = *(const GAS bf16x8*)(WGT + ((size_t)((dt * 8 + h) * 64 + cl)) * 64 + kk * 32 + 8 * fq);
;             __builtin_amdgcn_sched_barrier(0);
; #pragma unroll
;             for (int dt = 0; dt < 4; ++dt)
; #pragma unroll
;                 for (int kk = 0; kk < 2; ++kk) {
; #pragma unroll
;                     for (int mt = 0; mt < 4; ++mt) acc[mt][dt] = __builtin_amdgcn_mfma_f32_16x16x32_bf16(Af[mt][kk], Bfr[dt][kk], acc[mt][dt], 0, 0, 0); }
;             u32x2 abw[16];
; #pragma unroll
;             for (int d = 0; d < 2; ++d) {
;                 const float bgr = P.lru_bg[((l * 2 + d) * 2 + 0) * 512 + c], bgi = P.lru_bg[((l * 2 + d) * 2 + 1) * 512 + c];
;                 const float sp8 = SP8[(l * 2 + d) * 512 + c];
; #pragma unroll
;                 for (int mt = 0; mt < 4; ++mt)
; #pragma unroll
;                     for (int ip = 0; ip < 2; ++ip) { const int p = 16 * fq + 4 * mt + 2 * ip;
;                         const f32x2 xcv = (f32x2){bf2f(xcS[p * 72 + cl]), bf2f(xcS[(p + 1) * 72 + cl])};
;                         const f32x2 tr = ((f32x2){acc[mt][2 * d][2 * ip], acc[mt][2 * d][2 * ip + 1]} + bgr) * (-1.4426950408889634f);
;                         const f32x2 ti = ((f32x2){acc[mt][2 * d + 1][2 * ip], acc[mt][2 * d + 1][2 * ip + 1]} + bgi) * (-1.4426950408889634f);
;                         const f32x2 dr = (f32x2){__builtin_amdgcn_exp2f(tr.x), __builtin_amdgcn_exp2f(tr.y)} + 1.0f, di = (f32x2){__builtin_amdgcn_exp2f(ti.x), __builtin_amdgcn_exp2f(ti.y)} + 1.0f;
;                         const f32x2 r = (f32x2){__builtin_amdgcn_rcpf(dr.x), __builtin_amdgcn_rcpf(dr.y)}, ig = (f32x2){__builtin_amdgcn_rcpf(di.x), __builtin_amdgcn_rcpf(di.y)};
;                         const f32x2 la = r * (-sp8), x2 = la + la;
.LBB0_557:
	v_lshl_add_u64 v[224:225], v[154:155], 0, s[50:51]
	v_lshl_add_u64 v[226:227], v[150:151], 0, s[50:51]
	v_lshl_add_u64 v[228:229], s[92:93], 0, v[152:153]
	v_lshl_add_u64 v[230:231], s[92:93], 0, v[146:147]
	global_load_dword v218, v[224:225], off offset:-2048
	global_load_dword v219, v[224:225], off
	global_load_dword v220, v[228:229], off
	global_load_dword v221, v[226:227], off offset:-2048
	global_load_dword v222, v[226:227], off
	global_load_dword v223, v[230:231], off
	v_lshl_add_u64 v[52:53], s[92:93], 0, v[148:149]
	v_add_co_u32_e32 v36, vcc, 0x4e00000, v52
	s_nop 1
	v_addc_co_u32_e32 v37, vcc, 0, v53, vcc
	v_add_co_u32_e32 v44, vcc, 0x4e10000, v52
	global_load_dwordx4 v[32:35], v[36:37], off
	s_nop 0
	global_load_dwordx4 v[36:39], v[36:37], off offset:64
	v_addc_co_u32_e32 v45, vcc, 0, v53, vcc
	v_add_co_u32_e32 v54, vcc, 0x4e20000, v52
	global_load_dwordx4 v[40:43], v[44:45], off
	s_nop 0
	global_load_dwordx4 v[44:47], v[44:45], off offset:64
	v_addc_co_u32_e32 v55, vcc, 0, v53, vcc
	v_add_co_u32_e32 v52, vcc, 0x4e30000, v52
	global_load_dwordx4 v[48:51], v[54:55], off
	global_load_dwordx4 v[56:59], v[54:55], off offset:64
	v_addc_co_u32_e32 v53, vcc, 0, v53, vcc
	global_load_dwordx4 v[158:161], v[52:53], off
	global_load_dwordx4 v[162:165], v[52:53], off offset:64
	s_waitcnt vmcnt(7) lgkmcnt(7)
	v_mfma_f32_16x16x32_bf16 v[52:55], v[0:3], v[32:35], 0
	s_waitcnt lgkmcnt(5)
	v_mfma_f32_16x16x32_bf16 v[60:63], v[8:11], v[32:35], 0
	s_waitcnt lgkmcnt(3)
	v_mfma_f32_16x16x32_bf16 v[64:67], v[16:19], v[32:35], 0
	s_waitcnt lgkmcnt(1)
	v_mfma_f32_16x16x32_bf16 v[32:35], v[24:27], v[32:35], 0
	s_waitcnt vmcnt(6)
	v_mfma_f32_16x16x32_bf16 v[92:95], v[4:7], v[36:39], v[52:55]
	v_mfma_f32_16x16x32_bf16 v[84:87], v[12:15], v[36:39], v[60:63]
	v_mfma_f32_16x16x32_bf16 v[76:79], v[20:23], v[36:39], v[64:67]
	s_waitcnt lgkmcnt(0)
	v_mfma_f32_16x16x32_bf16 v[68:71], v[28:31], v[36:39], v[32:35]
	s_waitcnt vmcnt(5)
	v_mfma_f32_16x16x32_bf16 v[32:35], v[0:3], v[40:43], 0
	v_mfma_f32_16x16x32_bf16 v[36:39], v[8:11], v[40:43], 0
	v_mfma_f32_16x16x32_bf16 v[52:55], v[16:19], v[40:43], 0
	v_mfma_f32_16x16x32_bf16 v[40:43], v[24:27], v[40:43], 0
	s_waitcnt vmcnt(4)
	v_mfma_f32_16x16x32_bf16 v[88:91], v[4:7], v[44:47], v[32:35]
	v_mfma_f32_16x16x32_bf16 v[64:67], v[28:31], v[44:47], v[40:43]
	s_waitcnt vmcnt(3)
	v_mfma_f32_16x16x32_bf16 v[32:35], v[0:3], v[48:51], 0
	v_mfma_f32_16x16x32_bf16 v[40:43], v[16:19], v[48:51], 0
	v_mfma_f32_16x16x32_bf16 v[80:83], v[12:15], v[44:47], v[36:39]
	v_mfma_f32_16x16x32_bf16 v[72:75], v[20:23], v[44:47], v[52:55]
	v_mfma_f32_16x16x32_bf16 v[36:39], v[8:11], v[48:51], 0
	v_mfma_f32_16x16x32_bf16 v[48:51], v[24:27], v[48:51], 0
	s_waitcnt vmcnt(2)
	v_mfma_f32_16x16x32_bf16 v[60:63], v[4:7], v[56:59], v[32:35]
	v_mfma_f32_16x16x32_bf16 v[44:47], v[20:23], v[56:59], v[40:43]
	s_waitcnt vmcnt(1)
	v_mfma_f32_16x16x32_bf16 v[32:35], v[0:3], v[158:161], 0
	v_mfma_f32_16x16x32_bf16 v[40:43], v[8:11], v[158:161], 0
	v_mfma_f32_16x16x32_bf16 v[214:217], v[16:19], v[158:161], 0
	v_mfma_f32_16x16x32_bf16 v[158:161], v[24:27], v[158:161], 0
	v_mfma_f32_16x16x32_bf16 v[52:55], v[12:15], v[56:59], v[36:39]
	v_mfma_f32_16x16x32_bf16 v[36:39], v[28:31], v[56:59], v[48:51]
	s_waitcnt vmcnt(0)
	v_mfma_f32_16x16x32_bf16 v[56:59], v[4:7], v[162:165], v[32:35]
	v_mfma_f32_16x16x32_bf16 v[32:35], v[28:31], v[162:165], v[158:161]
	s_nop 2
	v_lshl_add_u64 v[158:159], v[154:155], 0, s[50:51]
	v_mov_b32_e32 v160, v218
	s_nop 0
	v_mov_b32_e32 v158, v219
	v_mfma_f32_16x16x32_bf16 v[48:51], v[12:15], v[162:165], v[40:43]
	s_waitcnt vmcnt(1)
	v_pk_add_f32 v[92:93], v[92:93], v[160:161] op_sel_hi:[1,0]
	v_mfma_f32_16x16x32_bf16 v[40:43], v[20:23], v[162:165], v[214:217]
	v_lshl_add_u64 v[162:163], s[92:93], 0, v[152:153]
	v_mov_b32_e32 v128, v220
	v_pk_mul_f32 v[92:93], v[92:93], s[18:19] op_sel_hi:[1,0]
	ds_read_u16 v159, v213
	ds_read_u16 v166, v213 offset:144
	v_exp_f32_e32 v92, v92
	v_exp_f32_e32 v93, v93
	s_nop 0
	v_pk_add_f32 v[92:93], v[92:93], 1.0 op_sel_hi:[1,0]
	s_nop 0
	v_rcp_f32_e32 v92, v92
	v_rcp_f32_e32 v93, v93
	s_waitcnt vmcnt(0)
	v_pk_mul_f32 v[92:93], v[128:129], v[92:93] op_sel_hi:[0,1] neg_lo:[1,0] neg_hi:[1,0]
	v_pk_add_f32 v[162:163], v[92:93], v[92:93]
	s_nop 0
	v_pk_fma_f32 v[164:165], v[162:163], s[20:21], v[136:137] op_sel_hi:[1,0,0]
	v_cmp_gt_f32_e64 s[46:47], s33, v162
	v_pk_fma_f32 v[164:165], v[162:163], v[164:165], s[22:23] op_sel_hi:[1,1,0]
	v_cmp_gt_f32_e64 s[44:45], s33, v163
	v_pk_fma_f32 v[164:165], v[162:163], v[164:165], 0.5 op_sel_hi:[1,1,0]
	s_or_b64 vcc, s[46:47], s[44:45]
	v_pk_fma_f32 v[164:165], v[162:163], v[164:165], 1.0 op_sel_hi:[1,1,0]
	s_nop 0
	v_pk_mul_f32 v[164:165], v[162:163], v[164:165] neg_lo:[0,1] neg_hi:[0,1]
	s_cbranch_vccnz .LBB0_577

; __device__ __forceinline__ float bf2f(unsigned short b) { return __uint_as_float(((unsigned)b) << 16); }
; __device__ __forceinline__ int lru_pass1(const Params& P, int l, LAS unsigned char* lds, unsigned* qw) {
;     ...
;             for (int d = 0; d < 2; ++d) {
;                 const float bgr = P.lru_bg[((l * 2 + d) * 2 + 0) * 512 + c], bgi = P.lru_bg[((l * 2 + d) * 2 + 1) * 512 + c];
;                 const float sp8 = SP8[(l * 2 + d) * 512 + c];
; #pragma unroll
;                 for (int mt = 0; mt < 4; ++mt)
; #pragma unroll
;                     for (int ip = 0; ip < 2; ++ip) { const int p = 16 * fq + 4 * mt + 2 * ip;
;                         const f32x2 xcv = (f32x2){bf2f(xcS[p * 72 + cl]), bf2f(xcS[(p + 1) * 72 + cl])};
;                         const f32x2 tr = ((f32x2){acc[mt][2 * d][2 * ip], acc[mt][2 * d][2 * ip + 1]} + bgr) * (-1.4426950408889634f);
;                         const f32x2 ti = ((f32x2){acc[mt][2 * d + 1][2 * ip], acc[mt][2 * d + 1][2 * ip + 1]} + bgi) * (-1.4426950408889634f);
;                         const f32x2 dr = (f32x2){__builtin_amdgcn_exp2f(tr.x), __builtin_amdgcn_exp2f(tr.y)} + 1.0f, di = (f32x2){__builtin_amdgcn_exp2f(ti.x), __builtin_amdgcn_exp2f(ti.y)} + 1.0f;
;                         const f32x2 r = (f32x2){__builtin_amdgcn_rcpf(dr.x), __builtin_amdgcn_rcpf(dr.y)}, ig = (f32x2){__builtin_amdgcn_rcpf(di.x), __builtin_amdgcn_rcpf(di.y)};
;                         const f32x2 la = r * (-sp8), x2 = la + la;
;                         f32x2 q5 = x2 * 0.0083333333f + 0.041666668f; q5 = q5 * x2 + 0.16666667f; q5 = q5 * x2 + 0.5f; q5 = q5 * x2 + 1.0f; f32x2 em = -(x2 * q5);
.LBB0_567:
	s_or_b64 exec, exec, s[8:9]
	v_lshl_add_u64 v[160:161], v[150:151], 0, s[50:51]
	v_mov_b32_e32 v162, v221
	v_lshl_add_u64 v[164:165], s[92:93], 0, v[146:147]
	v_mov_b32_e32 v128, v223
	s_nop 0
	v_mov_b32_e32 v160, v222
	s_waitcnt lgkmcnt(0)
	ds_read_u16 v65, v213
	ds_read_u16 v67, v213 offset:144
	s_waitcnt vmcnt(2)
	v_pk_add_f32 v[60:61], v[60:61], v[162:163] op_sel_hi:[1,0]
	s_nop 0
	v_pk_mul_f32 v[60:61], v[60:61], s[18:19] op_sel_hi:[1,0]
	s_nop 0
	v_exp_f32_e32 v60, v60
	v_exp_f32_e32 v61, v61
	s_nop 0
	v_pk_add_f32 v[60:61], v[60:61], 1.0 op_sel_hi:[1,0]
	s_nop 0
	v_rcp_f32_e32 v60, v60
	v_rcp_f32_e32 v61, v61
	s_waitcnt vmcnt(1)
	v_pk_mul_f32 v[164:165], v[128:129], v[60:61] op_sel_hi:[0,1] neg_lo:[1,0] neg_hi:[1,0]
	v_pk_add_f32 v[60:61], v[164:165], v[164:165]
	s_nop 0
	v_pk_fma_f32 v[166:167], v[60:61], s[20:21], v[136:137] op_sel_hi:[1,0,0]
	v_cmp_gt_f32_e64 s[46:47], s33, v60
	v_pk_fma_f32 v[166:167], v[60:61], v[166:167], s[22:23] op_sel_hi:[1,1,0]
	v_cmp_gt_f32_e64 s[44:45], s33, v61
	v_pk_fma_f32 v[166:167], v[60:61], v[166:167], 0.5 op_sel_hi:[1,1,0]
	s_or_b64 vcc, s[46:47], s[44:45]
	v_pk_fma_f32 v[166:167], v[60:61], v[166:167], 1.0 op_sel_hi:[1,1,0]
	s_nop 0
	v_pk_mul_f32 v[166:167], v[60:61], v[166:167] neg_lo:[0,1] neg_hi:[0,1]
	s_cbranch_vccnz .LBB0_601
